# v13: DSA/DA work items taken from per-XCD atomic queues (one batch / four heads per XCD, heavy first, stealing from other XCDs when empty) so workgroups of an XCD share K/V in L2
# speedup vs baseline: 1.0592x; 1.0070x over previous
; DI char* WS(const Params& P) { return P.ws + opaque0(); }
; DI void dsa_item(const Params& P, int layer, int b, int qt, char* mb, char* smem) {
;     ...
;   __syncthreads();
;   for (int i = tid; i < 4 * 129; i += 256) sbias[i] = ((const float*)(WS(P) + OFF_BIAS))[4 * 129 + i];
;   meta[tid] = (tid >= 32 && tid < 64) ? 256u : 0u;
; DI void phase_mix1(const Params& P, int layer, int bid, int nb, char* smem) {
;     ...
;   for (int j = 0;; j++) {
;     const int idx = (j & 1) ? (j * nb + (nb - 1 - bid)) : (j * nb + bid);
;     if (j * nb >= 2048) break;
;     if (idx >= 2048) continue;
;     const int qt = 255 - (idx >> 3), b = idx & 7;
;     dsa_item(P, layer, b, qt, mb, smem);
.LBB0_3227:
	s_waitcnt vmcnt(0) lgkmcnt(0)
	s_barrier
	v_readlane_b32 s4, v237, 9
	v_readlane_b32 s5, v237, 10
	s_mov_b64 s[0:1], exec
	s_and_b64 s[4:5], s[0:1], s[4:5]
	s_mov_b64 exec, s[4:5]
	s_cbranch_execz .Lq_dsa0_skip
	s_getreg_b32 s6, hwreg(HW_REG_XCC_ID, 0, 4)
	s_and_b32 s6, s6, 7
	s_mov_b32 s7, 0
.Lq_dsa0_retry:
	v_readlane_b32 s4, v237, 0
	v_readlane_b32 s5, v237, 1
	s_add_u32 s4, s4, 0x5589140
	s_addc_u32 s5, s5, 0
	s_lshl_b32 m0, s6, 4
	s_add_u32 s4, s4, m0
	s_addc_u32 s5, s5, 0
	v_mov_b32_e32 v238, 0
	v_mov_b32_e32 v239, 1
	global_atomic_add v239, v238, v239, s[4:5] sc0
	s_waitcnt vmcnt(0)
	s_nop 0
	v_readfirstlane_b32 s4, v239
	s_cmp_lt_u32 s4, 0x100
	s_cbranch_scc1 .Lq_dsa0_got
	s_add_i32 s6, s6, 1
	s_and_b32 s6, s6, 7
	s_add_i32 s7, s7, 1
	s_cmp_lt_u32 s7, 8
	s_cbranch_scc1 .Lq_dsa0_retry
	s_mov_b32 s4, 0xffff
.Lq_dsa0_got:
	s_lshl_b32 s6, s6, 16
	s_or_b32 s6, s6, s4
	v_mov_b32_e32 v239, s6
	v_mov_b32_e32 v238, 0x11ff8
	ds_write_b32 v238, v239
.Lq_dsa0_skip:
	s_mov_b64 exec, s[0:1]
	s_waitcnt lgkmcnt(0)
	s_barrier
	v_mov_b32_e32 v238, 0x11ff8
	ds_read_b32 v238, v238
	s_waitcnt lgkmcnt(0)
	s_nop 0
	v_readfirstlane_b32 s6, v238
	s_lshr_b32 s4, s6, 16
	s_and_b32 s6, s6, 0xffff
	s_lshl_b32 s5, s6, 3
	s_or_b32 s5, s5, s4
	s_cmpk_gt_i32 s6, 0xff
	s_cselect_b32 s6, 0x7fff, s5
	s_cmpk_gt_i32 s6, 0x7ff
	s_mov_b32 s7, 5
	s_cbranch_scc1 .LBB0_4105
	v_mov_b32_e32 v68, v202
	s_movk_i32 s0, 0x203
	s_mov_b64 s[72:73], 0
	v_cmp_lt_i32_e32 vcc, s0, v68
	v_ashrrev_i32_e32 v69, 31, v68
	v_add_u32_e32 v131, 0xffffff00, v68
	v_lshlrev_b32_e32 v85, 2, v68
	s_waitcnt vmcnt(0) lgkmcnt(0)
	s_barrier
	s_and_saveexec_b64 s[0:1], vcc
	s_xor_b64 s[0:1], exec, s[0:1]
	v_add_u32_e32 v131, 0xffffff00, v68
	v_lshlrev_b32_e32 v85, 2, v68
	s_andn2_saveexec_b64 s[0:1], s[0:1]
	s_cbranch_execz .LBB0_3235
	v_readlane_b32 s4, v236, 28
	v_mov_b32_e32 v4, v131
	s_nop 0
	v_add_u32_e32 v1, s4, v85
	v_readlane_b32 s4, v236, 26
	v_readlane_b32 s5, v236, 27
	s_nop 1
	v_lshl_add_u64 v[2:3], v[68:69], 2, s[4:5]
	s_mov_b64 s[4:5], 0

; DI char* WS(const Params& P) { return P.ws + opaque0(); }
; DI void da_item(const Params& P, int layer, int b, int h, int qt, char* mb, char* smem) {
;     ...
;   __syncthreads();
;   if (tid < 129) sbias[tid] = ((const float*)(WS(P) + OFF_BIAS))[h * 129 + tid] * LOG2E_;
; DI void phase_mix1(const Params& P, int layer, int bid, int nb, char* smem) {
;     ...
;   for (int j = 0;; j++) {
;     const int idx = (j & 1) ? (j * nb + (nb - 1 - bid)) : (j * nb + bid);
;     if (j * nb >= 2048) break;
;     if (idx >= 2048) continue;
;     const int qt = 63 - (idx >> 5), bh = idx & 31;
;     da_item(P, layer, bh >> 2, bh & 3, qt, mb, smem);
.LBB0_4111:
	s_waitcnt vmcnt(0) lgkmcnt(0)
	s_barrier
	v_readlane_b32 s4, v237, 9
	v_readlane_b32 s5, v237, 10
	s_mov_b64 s[22:23], exec
	s_and_b64 s[4:5], s[22:23], s[4:5]
	s_mov_b64 exec, s[4:5]
	s_cbranch_execz .Lq_da0_skip
	s_getreg_b32 s10, hwreg(HW_REG_XCC_ID, 0, 4)
	s_and_b32 s10, s10, 7
	s_mov_b32 s24, 0
.Lq_da0_retry:
	v_readlane_b32 s4, v237, 0
	v_readlane_b32 s5, v237, 1
	s_add_u32 s4, s4, 0x55891c0
	s_addc_u32 s5, s5, 0
	s_lshl_b32 m0, s10, 4
	s_add_u32 s4, s4, m0
	s_addc_u32 s5, s5, 0
	v_mov_b32_e32 v238, 0
	v_mov_b32_e32 v239, 1
	global_atomic_add v239, v238, v239, s[4:5] sc0
	s_waitcnt vmcnt(0)
	s_nop 0
	v_readfirstlane_b32 s4, v239
	s_cmp_lt_u32 s4, 0x100
	s_cbranch_scc1 .Lq_da0_got
	s_add_i32 s10, s10, 1
	s_and_b32 s10, s10, 7
	s_add_i32 s24, s24, 1
	s_cmp_lt_u32 s24, 8
	s_cbranch_scc1 .Lq_da0_retry
	s_mov_b32 s4, 0xffff
.Lq_da0_got:
	s_lshl_b32 s10, s10, 16
	s_or_b32 s10, s10, s4
	v_mov_b32_e32 v239, s10
	v_mov_b32_e32 v238, 0x11ff8
	ds_write_b32 v238, v239
.Lq_da0_skip:
	s_mov_b64 exec, s[22:23]
	s_waitcnt lgkmcnt(0)
	s_barrier
	v_mov_b32_e32 v238, 0x11ff8
	ds_read_b32 v238, v238
	s_waitcnt lgkmcnt(0)
	s_nop 0
	v_readfirstlane_b32 s10, v238
	s_lshr_b32 s4, s10, 16
	s_and_b32 s10, s10, 0xffff
	s_lshr_b32 s5, s10, 6
	s_lshl_b32 s5, s5, 3
	s_add_i32 s5, s5, s4
	s_and_b32 s4, s10, 63
	s_lshl_b32 s4, s4, 5
	s_or_b32 s4, s4, s5
	s_cmpk_gt_i32 s10, 0xff
	s_cselect_b32 s10, 0x7fff, s4
	s_mov_b32 s28, s10
	s_mov_b32 s38, 0
	s_cmpk_gt_i32 s10, 0x7ff
	s_mov_b32 s24, 8
	s_cbranch_scc1 .LBB0_4134
	v_mov_b32_e32 v3, v202
	s_and_b32 s24, s10, 3
	v_mov_b32_e32 v1, v202
	s_mov_b64 s[4:5], 0
	v_cmp_gt_i32_e32 vcc, s3, v3
	s_waitcnt vmcnt(0) lgkmcnt(0)
	s_barrier
	s_and_saveexec_b64 s[22:23], vcc
	s_cbranch_execz .LBB0_4115
	s_mov_b64 s[26:27], 0
	v_readlane_b32 s30, v237, 0
	s_mul_i32 s25, s24, 0x81
	v_readlane_b32 s31, v237, 1
	s_add_u32 s26, s30, s26
	v_add_u32_e32 v4, s25, v3
	s_addc_u32 s27, s31, s27
	v_ashrrev_i32_e32 v5, 31, v4
	v_lshl_add_u64 v[4:5], v[4:5], 2, s[26:27]
	v_add_co_u32_e32 v4, vcc, 0x5588000, v4
	s_nop 1
	v_addc_co_u32_e32 v5, vcc, 0, v5, vcc
	global_load_dword v4, v[4:5], off offset:256
	v_lshl_add_u32 v5, v3, 2, 0
	s_waitcnt vmcnt(0)
	v_mul_f32_e32 v4, 0x3fb8aa3b, v4
	ds_write_b32 v5, v4 offset:53248

; DI void phase_mix1(const Params& P, int layer, int bid, int nb, char* smem) {
;     ...
;   for (int j = 0;; j++) {
;     const int idx = (j & 1) ? (j * nb + (nb - 1 - bid)) : (j * nb + bid);
;     if (j * nb >= 2048) break;
;     if (idx >= 2048) continue;
;     const int qt = 255 - (idx >> 3), b = idx & 7;
;     dsa_item(P, layer, b, qt, mb, smem);
.Lq_dsa1_retry:
	v_readlane_b32 s4, v237, 0
	v_readlane_b32 s5, v237, 1
	s_add_u32 s4, s4, 0x5589240
	s_addc_u32 s5, s5, 0
	s_lshl_b32 m0, s6, 4
	s_add_u32 s4, s4, m0
	s_addc_u32 s5, s5, 0
	v_mov_b32_e32 v238, 0
	v_mov_b32_e32 v239, 1
	global_atomic_add v239, v238, v239, s[4:5] sc0
	s_waitcnt vmcnt(0)
	s_nop 0
	v_readfirstlane_b32 s4, v239
	s_cmp_lt_u32 s4, 0x100
	s_cbranch_scc1 .Lq_dsa1_got
	s_add_i32 s6, s6, 1
	s_and_b32 s6, s6, 7
	s_add_i32 s7, s7, 1
	s_cmp_lt_u32 s7, 8
	s_cbranch_scc1 .Lq_dsa1_retry
	s_mov_b32 s4, 0xffff

; DI char* WS(const Params& P) { return P.ws + opaque0(); }
; DI void dsa_item(const Params& P, int layer, int b, int qt, char* mb, char* smem) {
;     ...
;   __syncthreads();
;   for (int i = tid; i < 4 * 129; i += 256) sbias[i] = ((const float*)(WS(P) + OFF_BIAS))[4 * 129 + i];
;   meta[tid] = (tid >= 32 && tid < 64) ? 256u : 0u;
; DI void phase_mix1(const Params& P, int layer, int bid, int nb, char* smem) {
;     ...
;   for (int j = 0;; j++) {
;     const int idx = (j & 1) ? (j * nb + (nb - 1 - bid)) : (j * nb + bid);
;     if (j * nb >= 2048) break;
;     if (idx >= 2048) continue;
;     const int qt = 255 - (idx >> 3), b = idx & 7;
;     dsa_item(P, layer, b, qt, mb, smem);
.Lq_dsa1_skip:
	s_mov_b64 exec, s[0:1]
	s_waitcnt lgkmcnt(0)
	s_barrier
	v_mov_b32_e32 v238, 0x11ff8
	ds_read_b32 v238, v238
	s_waitcnt lgkmcnt(0)
	s_nop 0
	v_readfirstlane_b32 s6, v238
	s_lshr_b32 s4, s6, 16
	s_and_b32 s6, s6, 0xffff
	s_lshl_b32 s5, s6, 3
	s_or_b32 s5, s5, s4
	s_cmpk_gt_i32 s6, 0xff
	s_cselect_b32 s6, 0x7fff, s5
	s_cmpk_gt_i32 s6, 0x7ff
	s_mov_b32 s7, 5
	s_cbranch_scc1 .LBB0_8064
	v_mov_b32_e32 v68, v202
	s_movk_i32 s0, 0x203
	s_mov_b64 s[68:69], 0
	v_cmp_lt_i32_e32 vcc, s0, v68
	v_ashrrev_i32_e32 v69, 31, v68
	s_waitcnt vmcnt(0)
	v_add_u32_e32 v131, 0xffffff00, v68
	v_lshlrev_b32_e32 v85, 2, v68
	s_waitcnt lgkmcnt(0)
	s_barrier
	s_and_saveexec_b64 s[0:1], vcc
	s_xor_b64 s[0:1], exec, s[0:1]
	v_add_u32_e32 v131, 0xffffff00, v68
	v_lshlrev_b32_e32 v85, 2, v68
	s_andn2_saveexec_b64 s[0:1], s[0:1]
	s_cbranch_execz .LBB0_7194
	v_readlane_b32 s4, v236, 26
	v_mov_b32_e32 v4, v131
	s_nop 0
	v_add_u32_e32 v1, s4, v85
	v_readlane_b32 s4, v236, 22
	v_readlane_b32 s5, v236, 23
	s_nop 1
	v_lshl_add_u64 v[2:3], v[68:69], 2, s[4:5]
	s_mov_b64 s[4:5], 0

; DI void phase_mix1(const Params& P, int layer, int bid, int nb, char* smem) {
;     ...
;   for (int j = 0;; j++) {
;     const int idx = (j & 1) ? (j * nb + (nb - 1 - bid)) : (j * nb + bid);
;     if (j * nb >= 2048) break;
;     if (idx >= 2048) continue;
;     const int qt = 63 - (idx >> 5), bh = idx & 31;
;     da_item(P, layer, bh >> 2, bh & 3, qt, mb, smem);
.Lq_da1_retry:
	v_readlane_b32 s4, v237, 0
	v_readlane_b32 s5, v237, 1
	s_add_u32 s4, s4, 0x55892c0
	s_addc_u32 s5, s5, 0
	s_lshl_b32 m0, s10, 4
	s_add_u32 s4, s4, m0
	s_addc_u32 s5, s5, 0
	v_mov_b32_e32 v238, 0
	v_mov_b32_e32 v239, 1
	global_atomic_add v239, v238, v239, s[4:5] sc0
	s_waitcnt vmcnt(0)
	s_nop 0
	v_readfirstlane_b32 s4, v239
	s_cmp_lt_u32 s4, 0x100
	s_cbranch_scc1 .Lq_da1_got
	s_add_i32 s10, s10, 1
	s_and_b32 s10, s10, 7
	s_add_i32 s24, s24, 1
	s_cmp_lt_u32 s24, 8
	s_cbranch_scc1 .Lq_da1_retry
	s_mov_b32 s4, 0xffff

; DI char* WS(const Params& P) { return P.ws + opaque0(); }
; DI void da_item(const Params& P, int layer, int b, int h, int qt, char* mb, char* smem) {
;     ...
;   __syncthreads();
;   if (tid < 129) sbias[tid] = ((const float*)(WS(P) + OFF_BIAS))[h * 129 + tid] * LOG2E_;
; DI void phase_mix1(const Params& P, int layer, int bid, int nb, char* smem) {
;     ...
;   for (int j = 0;; j++) {
;     const int idx = (j & 1) ? (j * nb + (nb - 1 - bid)) : (j * nb + bid);
;     if (j * nb >= 2048) break;
;     if (idx >= 2048) continue;
;     const int qt = 63 - (idx >> 5), bh = idx & 31;
;     da_item(P, layer, bh >> 2, bh & 3, qt, mb, smem);
.Lq_da1_skip:
	s_mov_b64 exec, s[22:23]
	s_waitcnt lgkmcnt(0)
	s_barrier
	v_mov_b32_e32 v238, 0x11ff8
	ds_read_b32 v238, v238
	s_waitcnt lgkmcnt(0)
	s_nop 0
	v_readfirstlane_b32 s10, v238
	s_lshr_b32 s4, s10, 16
	s_and_b32 s10, s10, 0xffff
	s_lshr_b32 s5, s10, 6
	s_lshl_b32 s5, s5, 3
	s_add_i32 s5, s5, s4
	s_and_b32 s4, s10, 63
	s_lshl_b32 s4, s4, 5
	s_or_b32 s4, s4, s5
	s_cmpk_gt_i32 s10, 0xff
	s_cselect_b32 s10, 0x7fff, s4
	s_mov_b32 s28, s10
	s_mov_b32 s39, 0
	s_cmpk_gt_i32 s10, 0x7ff
	s_mov_b32 s24, 8
	s_cbranch_scc1 .LBB0_8093
	v_mov_b32_e32 v3, v202
	s_and_b32 s24, s10, 3
	v_mov_b32_e32 v1, v202
	s_mov_b64 s[4:5], 0
	v_cmp_gt_i32_e32 vcc, s3, v3
	s_waitcnt vmcnt(0) lgkmcnt(0)
	s_barrier
	s_and_saveexec_b64 s[22:23], vcc
	s_cbranch_execz .LBB0_8074
	s_mov_b64 s[26:27], 0
	v_readlane_b32 s30, v237, 0
	s_mul_i32 s25, s24, 0x81
	v_readlane_b32 s31, v237, 1
	s_add_u32 s26, s30, s26
	v_add_u32_e32 v4, s25, v3
	s_addc_u32 s27, s31, s27
	v_ashrrev_i32_e32 v5, 31, v4
	v_lshl_add_u64 v[4:5], v[4:5], 2, s[26:27]
	v_add_co_u32_e32 v4, vcc, 0x5588000, v4
	s_nop 1
	v_addc_co_u32_e32 v5, vcc, 0, v5, vcc
	global_load_dword v4, v[4:5], off offset:256
	v_lshl_add_u32 v5, v3, 2, 0
	s_waitcnt vmcnt(0)
	v_mul_f32_e32 v4, 0x3fb8aa3b, v4
	ds_write_b32 v5, v4 offset:53248
